# retention tile loop rebuilt as staggered compute/load segments: waves 0-3 and 4-7 alternate 16-MFMA segments with LDS-read segments, 8 barriers per tile
# baseline (speedup 1.0000x reference)
.LBB0_862:
	s_xor_b64 s[46:47], s[4:5], -1
	s_and_b64 s[4:5], s[4:5], exec
	v_mov_b32_e32 v20, v170
	s_cselect_b32 s9, s7, s8
	v_readfirstlane_b32 s4, v20
	s_ashr_i32 s4, s4, 2
	s_and_b32 s4, s4, -16
	v_and_b32_e32 v21, 15, v20
	s_add_i32 s4, s4, s9
	v_or_b32_e32 v172, s4, v21
	v_ashrrev_i32_e32 v173, 31, v172
	v_bfe_u32 v22, v20, 4, 2
	s_waitcnt lgkmcnt(0)
	v_lshlrev_b64 v[0:1], 14, v[172:173]
	v_lshl_add_u64 v[0:1], s[22:23], 0, v[0:1]
	v_lshlrev_b32_e32 v8, 4, v22
	v_lshl_add_u64 v[0:1], v[0:1], 0, v[8:9]
	v_mov_b32_e32 v16, v170
	global_load_dwordx4 v[102:105], v[0:1], off
	global_load_dwordx4 v[98:101], v[0:1], off offset:64
	global_load_dwordx4 v[94:97], v[0:1], off offset:128
	global_load_dwordx4 v[90:93], v[0:1], off offset:192
	global_load_dwordx4 v[86:89], v[0:1], off offset:256
	global_load_dwordx4 v[82:85], v[0:1], off offset:320
	global_load_dwordx4 v[78:81], v[0:1], off offset:384
	global_load_dwordx4 v[74:77], v[0:1], off offset:448
	v_mov_b32_e32 v23, v170
	v_lshlrev_b32_e32 v0, 4, v16
	v_and_b32_e32 v8, 0x1f0, v0
	v_lshl_add_u64 v[14:15], s[24:25], 0, v[8:9]
	v_lshrrev_b32_e32 v8, 5, v16
	v_lshlrev_b64 v[0:1], 14, v[8:9]
	v_lshl_add_u64 v[0:1], v[14:15], 0, v[0:1]
	v_add_u32_e32 v4, 0x200, v16
	global_load_dwordx4 v[0:3], v[0:1], off
	v_lshrrev_b32_e32 v8, 5, v4
	v_lshlrev_b64 v[4:5], 14, v[8:9]
	v_lshl_add_u64 v[4:5], v[14:15], 0, v[4:5]
	v_add_u32_e32 v8, 0x400, v16
	global_load_dwordx4 v[4:7], v[4:5], off
	v_lshrrev_b32_e32 v8, 5, v8
	v_lshlrev_b64 v[10:11], 14, v[8:9]
	v_lshl_add_u64 v[10:11], v[14:15], 0, v[10:11]
	v_add_u32_e32 v8, 0x600, v16
	global_load_dwordx4 v[10:13], v[10:11], off
	v_lshrrev_b32_e32 v8, 5, v8
	v_lshlrev_b64 v[16:17], 14, v[8:9]
	v_lshl_add_u64 v[14:15], v[14:15], 0, v[16:17]
	global_load_dwordx4 v[14:17], v[14:15], off
	v_lshlrev_b32_e32 v194, 2, v22
	v_lshlrev_b32_e32 v8, 4, v23
	v_and_b32_e32 v8, 0x1f0, v8
	v_lshrrev_b32_e32 v246, 1, v23
	v_and_b32_e32 v246, 0xf0, v246
	v_xor_b32_e32 v8, v8, v246
	v_add_u32_e32 v8, 0, v8
	v_lshrrev_b32_e32 v18, 5, v23
	v_mad_u64_u32 v[18:19], s[16:17], v18, s96, v[8:9]
	s_add_i32 s5, s9, 0x80
	v_readfirstlane_b32 s40, v179
	v_readfirstlane_b32 s44, v180
	v_readfirstlane_b32 s41, v181
	v_readfirstlane_b32 s37, v190
	v_readfirstlane_b32 s42, v191
	v_readfirstlane_b32 s36, v192
	v_readfirstlane_b32 s43, v193
	v_mov_b32_e32 v171, v172
	s_mov_b32 s45, 0
	s_mov_b32 s48, 0
	s_waitcnt vmcnt(3)
	ds_write_b128 v18, v[0:3]
	v_add_u32_e32 v0, 0x200, v23
	v_lshrrev_b32_e32 v0, 5, v0
	v_mad_u64_u32 v[0:1], s[16:17], v0, s96, v[8:9]
	s_waitcnt vmcnt(2)
	ds_write_b128 v0, v[4:7]
	v_add_u32_e32 v0, 0x400, v23
	v_lshrrev_b32_e32 v0, 5, v0
	v_mad_u64_u32 v[0:1], s[16:17], v0, s96, v[8:9]
	s_waitcnt vmcnt(1)
	ds_write_b128 v0, v[10:13]
	v_add_u32_e32 v0, 0x600, v23
	v_lshrrev_b32_e32 v0, 5, v0
	v_mad_u64_u32 v[0:1], s[16:17], v0, s96, v[8:9]
	s_waitcnt vmcnt(0)
	ds_write_b128 v0, v[14:17]
	v_mov_b32_e32 v16, v170
	v_mov_b32_e32 v23, v170
	v_lshlrev_b32_e32 v0, 4, v16
	v_and_b32_e32 v8, 0x1f0, v0
	v_lshl_add_u64 v[14:15], s[26:27], 0, v[8:9]
	v_lshrrev_b32_e32 v8, 5, v16
	v_lshlrev_b64 v[0:1], 14, v[8:9]
	v_lshl_add_u64 v[0:1], v[14:15], 0, v[0:1]
	v_add_u32_e32 v4, 0x200, v16
	global_load_dwordx4 v[0:3], v[0:1], off
	v_lshrrev_b32_e32 v8, 5, v4
	v_lshlrev_b64 v[4:5], 14, v[8:9]
	v_lshl_add_u64 v[4:5], v[14:15], 0, v[4:5]
	v_add_u32_e32 v8, 0x400, v16
	global_load_dwordx4 v[4:7], v[4:5], off
	v_lshrrev_b32_e32 v8, 5, v8
	v_lshlrev_b64 v[10:11], 14, v[8:9]
	v_lshl_add_u64 v[10:11], v[14:15], 0, v[10:11]
	v_add_u32_e32 v8, 0x600, v16
	global_load_dwordx4 v[10:13], v[10:11], off
	v_lshrrev_b32_e32 v8, 5, v8
	v_lshlrev_b64 v[16:17], 14, v[8:9]
	v_lshl_add_u64 v[14:15], v[14:15], 0, v[16:17]
	global_load_dwordx4 v[14:17], v[14:15], off
	s_nop 0
	v_lshlrev_b32_e32 v8, 4, v23
	v_and_b32_e32 v8, 0x1f0, v8
	v_lshrrev_b32_e32 v246, 5, v23
	v_and_b32_e32 v246, 7, v246
	v_lshlrev_b32_e32 v246, 5, v246
	v_xor_b32_e32 v8, v8, v246
	v_add_u32_e32 v8, s97, v8
	v_lshrrev_b32_e32 v18, 5, v23
	v_mad_u64_u32 v[18:19], s[16:17], v18, s96, v[8:9]
	s_waitcnt vmcnt(3)
	ds_write_b128 v18, v[0:3]
	v_add_u32_e32 v0, 0x200, v23
	v_lshrrev_b32_e32 v0, 5, v0
	v_mad_u64_u32 v[0:1], s[16:17], v0, s96, v[8:9]
	s_waitcnt vmcnt(2)
	ds_write_b128 v0, v[4:7]
	v_add_u32_e32 v0, 0x400, v23
	v_lshrrev_b32_e32 v0, 5, v0
	v_mad_u64_u32 v[0:1], s[16:17], v0, s96, v[8:9]
	s_waitcnt vmcnt(1)
	ds_write_b128 v0, v[10:13]
	v_add_u32_e32 v0, 0x600, v23
	v_lshrrev_b32_e32 v0, 5, v0
	v_mad_u64_u32 v[0:1], s[16:17], v0, s96, v[8:9]
	s_waitcnt vmcnt(0)
	ds_write_b128 v0, v[14:17]
	v_lshlrev_b32_e32 v0, 9, v21
	v_and_b32_e32 v1, 48, v20
	v_lshlrev_b32_e32 v246, 4, v21
	v_xor_b32_e32 v1, v1, v246
	v_add3_u32 v195, 0, v0, v1
	v_bfe_u32 v0, v20, 2, 2
	v_or_b32_e32 v0, v194, v0
	v_lshlrev_b32_e32 v1, 3, v20
	v_and_b32_e32 v246, 7, v0
	v_lshlrev_b32_e32 v246, 5, v246
	v_lshl_or_b32 v0, v0, 9, v246
	v_and_b32_e32 v1, 24, v1
	v_mov_b32_e32 v10, v9
	v_mov_b32_e32 v11, v9
	v_add3_u32 v173, s97, v0, v1
	v_add_u32_e32 v0, s4, v21
	v_mov_b32_e32 v8, v9
	v_mov_b64_e32 v[44:45], v[10:11]
	v_mov_b64_e32 v[48:49], v[10:11]
	v_mov_b64_e32 v[52:53], v[10:11]
	v_mov_b64_e32 v[56:57], v[10:11]
	v_mov_b64_e32 v[60:61], v[10:11]
	v_mov_b64_e32 v[64:65], v[10:11]
	v_mov_b64_e32 v[68:69], v[10:11]
	v_mov_b64_e32 v[72:73], v[10:11]
	v_mov_b64_e32 v[40:41], v[10:11]
	v_mov_b64_e32 v[36:37], v[10:11]
	v_mov_b64_e32 v[32:33], v[10:11]
	v_mov_b64_e32 v[28:29], v[10:11]
	v_mov_b64_e32 v[24:25], v[10:11]
	v_mov_b64_e32 v[20:21], v[10:11]
	v_mov_b64_e32 v[16:17], v[10:11]
	s_lshr_b32 s17, s5, 6
	v_mov_b64_e32 v[42:43], v[8:9]
	v_mov_b64_e32 v[46:47], v[8:9]
	v_mov_b64_e32 v[50:51], v[8:9]
	v_mov_b64_e32 v[54:55], v[8:9]
	v_mov_b64_e32 v[58:59], v[8:9]
	v_mov_b64_e32 v[62:63], v[8:9]
	v_mov_b64_e32 v[66:67], v[8:9]
	v_mov_b64_e32 v[70:71], v[8:9]
	v_mov_b64_e32 v[38:39], v[8:9]
	v_mov_b64_e32 v[34:35], v[8:9]
	v_mov_b64_e32 v[30:31], v[8:9]
	v_mov_b64_e32 v[26:27], v[8:9]
	v_mov_b64_e32 v[22:23], v[8:9]
	v_mov_b64_e32 v[18:19], v[8:9]
	v_mov_b64_e32 v[14:15], v[8:9]
	v_mov_b64_e32 v[12:13], v[10:11]
	s_or_b32 s16, s4, 15
	s_add_i32 s17, s17, -1
	v_sub_u32_e32 v196, v0, v194
	v_mov_b64_e32 v[10:11], v[8:9]
	v_lshrrev_b32_e32 v106, 5, v170
	v_and_b32_e32 v107, 31, v170
	v_and_b32_e32 v108, 15, v106
	v_xor_b32_e32 v108, v107, v108
	v_and_b32_e32 v109, 7, v106
	v_lshlrev_b32_e32 v109, 1, v109
	v_xor_b32_e32 v107, v107, v109
	v_lshlrev_b32_e32 v109, 14, v106
	v_lshl_or_b32 v106, v108, 4, v109
	v_lshl_or_b32 v107, v107, 4, v109
	s_waitcnt lgkmcnt(0)
	s_barrier
	v_readlane_b32 s4, v254, 60
	s_cmp_lt_u32 s4, 4
	s_cbranch_scc1 .Lr_nostag
	s_barrier
.Lr_nostag:
	s_branch .LBB0_865
.LBB0_863:
	v_cvt_pk_bf16_f32 v6, v174, v175
	v_cvt_pk_bf16_f32 v7, v176, v177
	s_nop 1
	ds_read_b64_tr_b16 v[116:117], v115
	ds_read_b64_tr_b16 v[118:119], v115 offset:8192
	ds_read_b64_tr_b16 v[120:121], v108
	ds_read_b64_tr_b16 v[122:123], v108 offset:8192
	ds_read_b64_tr_b16 v[124:125], v109
	ds_read_b64_tr_b16 v[126:127], v109 offset:8192
	ds_read_b64_tr_b16 v[128:129], v110
	ds_read_b64_tr_b16 v[130:131], v110 offset:8192
	ds_read_b64_tr_b16 v[174:175], v111
	ds_read_b64_tr_b16 v[176:177], v111 offset:8192
	ds_read_b64_tr_b16 v[198:199], v112
	ds_read_b64_tr_b16 v[200:201], v112 offset:8192
	ds_read_b64_tr_b16 v[202:203], v113
	ds_read_b64_tr_b16 v[204:205], v113 offset:8192
	ds_read_b64_tr_b16 v[206:207], v114
	ds_read_b64_tr_b16 v[208:209], v114 offset:8192
	ds_read_b64_tr_b16 v[210:211], v115 offset:256
	ds_read_b64_tr_b16 v[212:213], v115 offset:8448
	ds_read_b64_tr_b16 v[214:215], v108 offset:256
	ds_read_b64_tr_b16 v[216:217], v108 offset:8448
	ds_read_b64_tr_b16 v[218:219], v109 offset:256
	ds_read_b64_tr_b16 v[220:221], v109 offset:8448
	ds_read_b64_tr_b16 v[226:227], v110 offset:256
	ds_read_b64_tr_b16 v[228:229], v110 offset:8448
	ds_read_b64_tr_b16 v[230:231], v111 offset:256
	ds_read_b64_tr_b16 v[232:233], v111 offset:8448
	ds_read_b64_tr_b16 v[234:235], v112 offset:256
	ds_read_b64_tr_b16 v[236:237], v112 offset:8448
	ds_read_b64_tr_b16 v[238:239], v113 offset:256
	ds_read_b64_tr_b16 v[240:241], v113 offset:8448
	ds_read_b64_tr_b16 v[242:243], v114 offset:256
	ds_read_b64_tr_b16 v[244:245], v114 offset:8448
	s_waitcnt lgkmcnt(0)
	s_barrier
	v_mfma_f32_16x16x32_bf16 v[70:73], v[116:119], v[0:3], v[70:73]
	v_mfma_f32_16x16x32_bf16 v[66:69], v[120:123], v[0:3], v[66:69]
	v_mfma_f32_16x16x32_bf16 v[62:65], v[124:127], v[0:3], v[62:65]
	v_mfma_f32_16x16x32_bf16 v[58:61], v[128:131], v[0:3], v[58:61]
	v_mfma_f32_16x16x32_bf16 v[54:57], v[174:177], v[0:3], v[54:57]
	v_mfma_f32_16x16x32_bf16 v[50:53], v[198:201], v[0:3], v[50:53]
	v_mfma_f32_16x16x32_bf16 v[46:49], v[202:205], v[0:3], v[46:49]
	v_mfma_f32_16x16x32_bf16 v[42:45], v[206:209], v[0:3], v[42:45]
	v_mfma_f32_16x16x32_bf16 v[38:41], v[210:213], v[0:3], v[38:41]
	v_mfma_f32_16x16x32_bf16 v[34:37], v[214:217], v[0:3], v[34:37]
	v_mfma_f32_16x16x32_bf16 v[30:33], v[218:221], v[0:3], v[30:33]
	v_mfma_f32_16x16x32_bf16 v[26:29], v[226:229], v[0:3], v[26:29]
	v_mfma_f32_16x16x32_bf16 v[22:25], v[230:233], v[0:3], v[22:25]
	v_mfma_f32_16x16x32_bf16 v[18:21], v[234:237], v[0:3], v[18:21]
	v_mfma_f32_16x16x32_bf16 v[14:17], v[238:241], v[0:3], v[14:17]
	v_mfma_f32_16x16x32_bf16 v[10:13], v[242:245], v[0:3], v[10:13]
	s_barrier
	ds_read_b64_tr_b16 v[116:117], v115 offset:16384
	ds_read_b64_tr_b16 v[118:119], v115 offset:24576
	ds_read_b64_tr_b16 v[120:121], v108 offset:16384
	ds_read_b64_tr_b16 v[122:123], v108 offset:24576
	ds_read_b64_tr_b16 v[124:125], v109 offset:16384
	ds_read_b64_tr_b16 v[126:127], v109 offset:24576
	ds_read_b64_tr_b16 v[128:129], v110 offset:16384
	ds_read_b64_tr_b16 v[130:131], v110 offset:24576
	ds_read_b64_tr_b16 v[174:175], v111 offset:16384
	ds_read_b64_tr_b16 v[176:177], v111 offset:24576
	ds_read_b64_tr_b16 v[198:199], v112 offset:16384
	ds_read_b64_tr_b16 v[200:201], v112 offset:24576
	ds_read_b64_tr_b16 v[202:203], v113 offset:16384
	ds_read_b64_tr_b16 v[204:205], v113 offset:24576
	ds_read_b64_tr_b16 v[206:207], v114 offset:16384
	ds_read_b64_tr_b16 v[208:209], v114 offset:24576
	ds_read_b64_tr_b16 v[210:211], v115 offset:16640
	ds_read_b64_tr_b16 v[212:213], v115 offset:24832
	ds_read_b64_tr_b16 v[214:215], v108 offset:16640
	ds_read_b64_tr_b16 v[216:217], v108 offset:24832
	ds_read_b64_tr_b16 v[218:219], v109 offset:16640
	ds_read_b64_tr_b16 v[220:221], v109 offset:24832
	ds_read_b64_tr_b16 v[226:227], v110 offset:16640
	ds_read_b64_tr_b16 v[228:229], v110 offset:24832
	ds_read_b64_tr_b16 v[230:231], v111 offset:16640
	ds_read_b64_tr_b16 v[232:233], v111 offset:24832
	ds_read_b64_tr_b16 v[234:235], v112 offset:16640
	ds_read_b64_tr_b16 v[236:237], v112 offset:24832
	ds_read_b64_tr_b16 v[238:239], v113 offset:16640
	ds_read_b64_tr_b16 v[240:241], v113 offset:24832
	ds_read_b64_tr_b16 v[242:243], v114 offset:16640
	ds_read_b64_tr_b16 v[244:245], v114 offset:24832
	s_waitcnt vmcnt(0) lgkmcnt(0)
	s_barrier
	v_mfma_f32_16x16x32_bf16 v[70:73], v[116:119], v[4:7], v[70:73]
	v_mfma_f32_16x16x32_bf16 v[66:69], v[120:123], v[4:7], v[66:69]
	v_mfma_f32_16x16x32_bf16 v[62:65], v[124:127], v[4:7], v[62:65]
	v_mfma_f32_16x16x32_bf16 v[58:61], v[128:131], v[4:7], v[58:61]
	v_mfma_f32_16x16x32_bf16 v[54:57], v[174:177], v[4:7], v[54:57]
	v_mfma_f32_16x16x32_bf16 v[50:53], v[198:201], v[4:7], v[50:53]
	v_mfma_f32_16x16x32_bf16 v[46:49], v[202:205], v[4:7], v[46:49]
	v_mfma_f32_16x16x32_bf16 v[42:45], v[206:209], v[4:7], v[42:45]
	v_mfma_f32_16x16x32_bf16 v[38:41], v[210:213], v[4:7], v[38:41]
	v_mfma_f32_16x16x32_bf16 v[34:37], v[214:217], v[4:7], v[34:37]
	v_mfma_f32_16x16x32_bf16 v[30:33], v[218:221], v[4:7], v[30:33]
	v_mfma_f32_16x16x32_bf16 v[26:29], v[226:229], v[4:7], v[26:29]
	v_mfma_f32_16x16x32_bf16 v[22:25], v[230:233], v[4:7], v[22:25]
	v_mfma_f32_16x16x32_bf16 v[18:21], v[234:237], v[4:7], v[18:21]
	v_mfma_f32_16x16x32_bf16 v[14:17], v[238:241], v[4:7], v[14:17]
	v_mfma_f32_16x16x32_bf16 v[10:13], v[242:245], v[4:7], v[10:13]
.LBB0_864:
	s_add_i32 s48, s48, 1
	s_add_i32 s45, s45, 64
	s_cmp_eq_u32 s17, s48
	v_subrev_u32_e32 v196, 64, v196
	s_barrier
	s_cbranch_scc1 .Lr_exit
.LBB0_865:
	s_and_b32 s49, s48, 1
	s_mul_i32 s4, s49, 0x8400
	v_add_u32_e32 v8, s4, v195
	v_xor_b32_e32 v246, 64, v8
	v_xor_b32_e32 v247, 0x80, v8
	v_xor_b32_e32 v248, 0xc0, v8
	ds_read_b128 v[0:3], v8
	ds_read_b128 v[4:7], v8 offset:8192
	ds_read_b128 v[174:177], v8 offset:16384
	ds_read_b128 v[198:201], v8 offset:24576
	ds_read_b128 v[202:205], v246
	ds_read_b128 v[206:209], v246 offset:8192
	ds_read_b128 v[210:213], v246 offset:16384
	ds_read_b128 v[214:217], v246 offset:24576
	ds_read_b128 v[218:221], v247
	ds_read_b128 v[226:229], v247 offset:8192
	ds_read_b128 v[230:233], v247 offset:16384
	ds_read_b128 v[234:237], v247 offset:24576
	ds_read_b128 v[238:241], v248
	ds_read_b128 v[242:245], v248 offset:8192
	ds_read_b128 v[116:119], v248 offset:16384
	ds_read_b128 v[120:123], v248 offset:24576
	s_mul_i32 s5, s49, 0x8800
	v_add_u32_e32 v115, s5, v173
	v_xor_b32_e32 v108, 0x20, v115
	v_xor_b32_e32 v109, 0x40, v115
	v_xor_b32_e32 v110, 0x60, v115
	v_xor_b32_e32 v111, 0x80, v115
	v_xor_b32_e32 v112, 0xa0, v115
	v_xor_b32_e32 v113, 0xc0, v115
	v_xor_b32_e32 v114, 0xe0, v115
	s_waitcnt lgkmcnt(0)
	s_barrier
	v_mfma_f32_16x16x32_bf16 v[150:153], v[0:3], v[102:105], 0
	v_mfma_f32_16x16x32_bf16 v[146:149], v[4:7], v[102:105], 0
	v_mfma_f32_16x16x32_bf16 v[142:145], v[174:177], v[102:105], 0
	v_mfma_f32_16x16x32_bf16 v[138:141], v[198:201], v[102:105], 0
	v_mfma_f32_16x16x32_bf16 v[150:153], v[202:205], v[98:101], v[150:153]
	v_mfma_f32_16x16x32_bf16 v[146:149], v[206:209], v[98:101], v[146:149]
	v_mfma_f32_16x16x32_bf16 v[142:145], v[210:213], v[98:101], v[142:145]
	v_mfma_f32_16x16x32_bf16 v[138:141], v[214:217], v[98:101], v[138:141]
	v_mfma_f32_16x16x32_bf16 v[150:153], v[218:221], v[94:97], v[150:153]
	v_mfma_f32_16x16x32_bf16 v[146:149], v[226:229], v[94:97], v[146:149]
	v_mfma_f32_16x16x32_bf16 v[142:145], v[230:233], v[94:97], v[142:145]
	v_mfma_f32_16x16x32_bf16 v[138:141], v[234:237], v[94:97], v[138:141]
	v_mfma_f32_16x16x32_bf16 v[150:153], v[238:241], v[90:93], v[150:153]
	v_mfma_f32_16x16x32_bf16 v[146:149], v[242:245], v[90:93], v[146:149]
	v_mfma_f32_16x16x32_bf16 v[142:145], v[116:119], v[90:93], v[142:145]
	v_mfma_f32_16x16x32_bf16 v[138:141], v[120:123], v[90:93], v[138:141]
	s_barrier
	ds_read_b128 v[0:3], v8 offset:256
	ds_read_b128 v[4:7], v8 offset:8448
	ds_read_b128 v[174:177], v8 offset:16640
	ds_read_b128 v[198:201], v8 offset:24832
	ds_read_b128 v[202:205], v246 offset:256
	ds_read_b128 v[206:209], v246 offset:8448
	ds_read_b128 v[210:213], v246 offset:16640
	ds_read_b128 v[214:217], v246 offset:24832
	ds_read_b128 v[218:221], v247 offset:256
	ds_read_b128 v[226:229], v247 offset:8448
	ds_read_b128 v[230:233], v247 offset:16640
	ds_read_b128 v[234:237], v247 offset:24832
	ds_read_b128 v[238:241], v248 offset:256
	ds_read_b128 v[242:245], v248 offset:8448
	ds_read_b128 v[116:119], v248 offset:16640
	ds_read_b128 v[120:123], v248 offset:24832
	s_lshl_b32 s4, s45, 14
	s_add_i32 s4, s4, 0x100000
	v_readlane_b32 s5, v254, 60
	s_lshl_b32 s5, s5, 10
	s_cmp_eq_u32 s49, 0
	s_cselect_b32 m0, 0x8400, 0
	s_add_i32 m0, m0, s5
	v_add_u32_e32 v132, s4, v106
	v_add_u32_e32 v136, s4, v107
	s_add_i32 s4, s4, 0x40000
	v_add_u32_e32 v133, s4, v106
	v_add_u32_e32 v137, s4, v107
	s_add_i32 s4, s4, 0x40000
	v_add_u32_e32 v134, s4, v106
	v_add_u32_e32 v246, s4, v107
	s_add_i32 s4, s4, 0x40000
	v_add_u32_e32 v135, s4, v106
	v_add_u32_e32 v247, s4, v107
	global_load_lds_dwordx4 v132, s[24:25]
	s_add_i32 m0, m0, 0x2000
	s_nop 0
	global_load_lds_dwordx4 v133, s[24:25]
	s_add_i32 m0, m0, 0x2000
	s_nop 0
	global_load_lds_dwordx4 v134, s[24:25]
	s_add_i32 m0, m0, 0x2000
	s_nop 0
	global_load_lds_dwordx4 v135, s[24:25]
	s_cmp_eq_u32 s49, 0
	s_cselect_b32 m0, 0x8800, 0
	s_add_i32 m0, m0, s5
	s_add_i32 m0, m0, 0x10800
	s_nop 0
	global_load_lds_dwordx4 v136, s[26:27]
	s_add_i32 m0, m0, 0x2000
	s_nop 0
	global_load_lds_dwordx4 v137, s[26:27]
	s_add_i32 m0, m0, 0x2000
	s_nop 0
	global_load_lds_dwordx4 v246, s[26:27]
	s_add_i32 m0, m0, 0x2000
	s_nop 0
	global_load_lds_dwordx4 v247, s[26:27]
	s_waitcnt lgkmcnt(0)
	s_barrier
	v_mfma_f32_16x16x32_bf16 v[150:153], v[0:3], v[86:89], v[150:153]
	v_mfma_f32_16x16x32_bf16 v[146:149], v[4:7], v[86:89], v[146:149]
	v_mfma_f32_16x16x32_bf16 v[142:145], v[174:177], v[86:89], v[142:145]
	v_mfma_f32_16x16x32_bf16 v[138:141], v[198:201], v[86:89], v[138:141]
	v_mfma_f32_16x16x32_bf16 v[150:153], v[202:205], v[82:85], v[150:153]
	v_mfma_f32_16x16x32_bf16 v[146:149], v[206:209], v[82:85], v[146:149]
	v_mfma_f32_16x16x32_bf16 v[142:145], v[210:213], v[82:85], v[142:145]
	v_mfma_f32_16x16x32_bf16 v[138:141], v[214:217], v[82:85], v[138:141]
	v_mfma_f32_16x16x32_bf16 v[150:153], v[218:221], v[78:81], v[150:153]
	v_mfma_f32_16x16x32_bf16 v[146:149], v[226:229], v[78:81], v[146:149]
	v_mfma_f32_16x16x32_bf16 v[142:145], v[230:233], v[78:81], v[142:145]
	v_mfma_f32_16x16x32_bf16 v[138:141], v[234:237], v[78:81], v[138:141]
	v_mfma_f32_16x16x32_bf16 v[150:153], v[238:241], v[74:77], v[150:153]
	v_mfma_f32_16x16x32_bf16 v[146:149], v[242:245], v[74:77], v[146:149]
	v_mfma_f32_16x16x32_bf16 v[142:145], v[116:119], v[74:77], v[142:145]
	v_mfma_f32_16x16x32_bf16 v[138:141], v[120:123], v[74:77], v[138:141]
	s_barrier
	s_add_i32 s4, s45, 63
	s_cmp_le_u32 s4, s9
	s_mov_b64 s[4:5], -1
	s_cbranch_scc0 .LBB0_868
	v_cvt_f32_i32_e32 v0, v196
	s_mov_b64 s[4:5], 0
	v_mul_f32_e32 v0, v178, v0
	v_exp_f32_e32 v8, v0
	s_nop 0
	v_mul_f32_e32 v0, s40, v8
	v_pk_mul_f32 v[2:3], s[40:41], v[0:1] op_sel_hi:[1,0]
	v_pk_mul_f32 v[0:1], s[42:43], v[0:1] op_sel_hi:[1,0]
	v_pk_mul_f32 v[2:3], v[2:3], v[150:151]
	v_pk_mul_f32 v[4:5], v[0:1], v[152:153]
	v_cvt_pk_bf16_f32 v0, v2, v3
	v_mul_f32_e32 v2, s44, v8
	v_cvt_pk_bf16_f32 v1, v4, v5
	v_pk_mul_f32 v[4:5], s[40:41], v[2:3] op_sel_hi:[1,0]
	v_pk_mul_f32 v[2:3], s[42:43], v[2:3] op_sel_hi:[1,0]
	v_pk_mul_f32 v[4:5], v[4:5], v[146:147]
	v_pk_mul_f32 v[6:7], v[2:3], v[148:149]
	v_cvt_pk_bf16_f32 v2, v4, v5
	v_mul_f32_e32 v4, s37, v8
	v_cvt_pk_bf16_f32 v3, v6, v7
	v_pk_mul_f32 v[6:7], s[40:41], v[4:5] op_sel_hi:[1,0]
	v_pk_mul_f32 v[4:5], s[42:43], v[4:5] op_sel_hi:[1,0]
	v_pk_mul_f32 v[6:7], v[6:7], v[142:143]
	v_pk_mul_f32 v[154:155], v[4:5], v[144:145]
	v_cvt_pk_bf16_f32 v4, v6, v7
	v_mul_f32_e32 v6, s36, v8
	v_cvt_pk_bf16_f32 v5, v154, v155
	v_pk_mul_f32 v[154:155], s[40:41], v[6:7] op_sel_hi:[1,0]
	v_pk_mul_f32 v[6:7], s[42:43], v[6:7] op_sel_hi:[1,0]
	v_pk_mul_f32 v[174:175], v[154:155], v[138:139]
	v_pk_mul_f32 v[176:177], v[6:7], v[140:141]

.Lr_exit:
	v_readlane_b32 s4, v254, 60
	s_cmp_ge_u32 s4, 4
	s_cbranch_scc1 .Lr_exdone
	s_barrier
.Lr_exdone:
.LBB0_870:
	s_cmp_gt_i32 s45, s16
	s_cbranch_scc1 .LBB0_861
	s_and_b32 s16, s17, 1
	s_mul_i32 s4, s16, 0x8400
	v_add_u32_e32 v8, s4, v195
	v_xor_b32_e32 v246, 64, v8
	v_xor_b32_e32 v247, 0x80, v8
	v_xor_b32_e32 v248, 0xc0, v8
	ds_read_b128 v[0:3], v8
	ds_read_b128 v[4:7], v8 offset:8192
	ds_read_b128 v[106:109], v246
	ds_read_b128 v[110:113], v8 offset:16384
	ds_read_b128 v[114:117], v246 offset:8192
	ds_read_b128 v[118:121], v8 offset:24576
	ds_read_b128 v[122:125], v246 offset:16384
	s_waitcnt lgkmcnt(6)
	v_mfma_f32_16x16x32_bf16 v[0:3], v[0:3], v[102:105], 0
	ds_read_b128 v[126:129], v246 offset:24576
	s_or_b32 s4, s45, 63
	s_cmp_gt_u32 s4, s9
	s_waitcnt lgkmcnt(6)
	v_mfma_f32_16x16x32_bf16 v[4:7], v[4:7], v[102:105], 0
	s_waitcnt lgkmcnt(4)
	v_mfma_f32_16x16x32_bf16 v[110:113], v[110:113], v[102:105], 0
	s_waitcnt lgkmcnt(2)
	v_mfma_f32_16x16x32_bf16 v[102:105], v[118:121], v[102:105], 0
	v_mfma_f32_16x16x32_bf16 v[0:3], v[106:109], v[98:101], v[0:3]
	v_mfma_f32_16x16x32_bf16 v[4:7], v[114:117], v[98:101], v[4:7]
	s_waitcnt lgkmcnt(1)
	v_mfma_f32_16x16x32_bf16 v[106:109], v[122:125], v[98:101], v[110:113]
	s_nop 2
	ds_read_b128 v[110:113], v247 offset:24576
	ds_read_b128 v[114:117], v247 offset:16384
	ds_read_b128 v[118:121], v247 offset:8192
	ds_read_b128 v[122:125], v247
	s_waitcnt lgkmcnt(4)
	v_mfma_f32_16x16x32_bf16 v[98:101], v[126:129], v[98:101], v[102:105]
	s_waitcnt lgkmcnt(0)
	v_mfma_f32_16x16x32_bf16 v[0:3], v[122:125], v[94:97], v[0:3]
	v_mfma_f32_16x16x32_bf16 v[4:7], v[118:121], v[94:97], v[4:7]
	v_mfma_f32_16x16x32_bf16 v[102:105], v[114:117], v[94:97], v[106:109]
	s_nop 2
	ds_read_b128 v[106:109], v248
	ds_read_b128 v[114:117], v248 offset:8192
	ds_read_b128 v[118:121], v248 offset:16384
	ds_read_b128 v[122:125], v248 offset:24576
	v_mfma_f32_16x16x32_bf16 v[94:97], v[110:113], v[94:97], v[98:101]
	s_waitcnt lgkmcnt(3)
	v_mfma_f32_16x16x32_bf16 v[0:3], v[106:109], v[90:93], v[0:3]
	s_waitcnt lgkmcnt(2)
	v_mfma_f32_16x16x32_bf16 v[4:7], v[114:117], v[90:93], v[4:7]
	s_waitcnt lgkmcnt(1)
	v_mfma_f32_16x16x32_bf16 v[98:101], v[118:121], v[90:93], v[102:105]
	s_nop 2
	ds_read_b128 v[102:105], v8 offset:24832
	ds_read_b128 v[106:109], v8 offset:16640
	ds_read_b128 v[110:113], v8 offset:8448
	ds_read_b128 v[114:117], v8 offset:256
	s_waitcnt lgkmcnt(4)
	v_mfma_f32_16x16x32_bf16 v[90:93], v[122:125], v[90:93], v[94:97]
	s_waitcnt lgkmcnt(0)
	v_mfma_f32_16x16x32_bf16 v[0:3], v[114:117], v[86:89], v[0:3]
	v_mfma_f32_16x16x32_bf16 v[4:7], v[110:113], v[86:89], v[4:7]
	v_mfma_f32_16x16x32_bf16 v[94:97], v[106:109], v[86:89], v[98:101]
	s_nop 2
	ds_read_b128 v[98:101], v246 offset:256
	ds_read_b128 v[106:109], v246 offset:8448
	ds_read_b128 v[110:113], v246 offset:16640
	ds_read_b128 v[114:117], v246 offset:24832
	v_mfma_f32_16x16x32_bf16 v[86:89], v[102:105], v[86:89], v[90:93]
	s_waitcnt lgkmcnt(3)
	v_mfma_f32_16x16x32_bf16 v[0:3], v[98:101], v[82:85], v[0:3]
	s_waitcnt lgkmcnt(2)
	v_mfma_f32_16x16x32_bf16 v[4:7], v[106:109], v[82:85], v[4:7]
	s_waitcnt lgkmcnt(1)
	v_mfma_f32_16x16x32_bf16 v[90:93], v[110:113], v[82:85], v[94:97]
	s_nop 2
	ds_read_b128 v[94:97], v247 offset:24832
	ds_read_b128 v[98:101], v247 offset:16640
	ds_read_b128 v[102:105], v247 offset:8448
	ds_read_b128 v[106:109], v247 offset:256
	s_waitcnt lgkmcnt(4)
	v_mfma_f32_16x16x32_bf16 v[82:85], v[114:117], v[82:85], v[86:89]
	s_waitcnt lgkmcnt(0)
	v_mfma_f32_16x16x32_bf16 v[0:3], v[106:109], v[78:81], v[0:3]
	v_mfma_f32_16x16x32_bf16 v[4:7], v[102:105], v[78:81], v[4:7]
	v_mfma_f32_16x16x32_bf16 v[90:93], v[98:101], v[78:81], v[90:93]
	ds_read_b128 v[86:89], v248 offset:256
	ds_read_b128 v[98:101], v248 offset:8448
	ds_read_b128 v[102:105], v248 offset:16640
	ds_read_b128 v[106:109], v248 offset:24832
	v_mfma_f32_16x16x32_bf16 v[94:97], v[94:97], v[78:81], v[82:85]
	s_waitcnt lgkmcnt(3)
	v_mfma_f32_16x16x32_bf16 v[86:89], v[86:89], v[74:77], v[0:3]
	s_waitcnt lgkmcnt(2)
	v_mfma_f32_16x16x32_bf16 v[82:85], v[98:101], v[74:77], v[4:7]
	s_waitcnt lgkmcnt(1)
	v_mfma_f32_16x16x32_bf16 v[78:81], v[102:105], v[74:77], v[90:93]
	s_waitcnt lgkmcnt(0)
	v_mfma_f32_16x16x32_bf16 v[74:77], v[106:109], v[74:77], v[94:97]
	v_or_b32_e32 v8, s45, v194
	s_nop 1
	v_sub_u32_e32 v94, v172, v8
	s_mov_b64 s[4:5], -1
	s_cbranch_scc1 .LBB0_873
	v_cvt_f32_i32_e32 v0, v94
	s_mov_b64 s[4:5], 0
	v_mul_f32_e32 v0, v178, v0
	v_exp_f32_e32 v92, v0
	s_nop 0
	v_mul_f32_e32 v0, s40, v92
	v_pk_mul_f32 v[2:3], s[40:41], v[0:1] op_sel_hi:[1,0]
	v_pk_mul_f32 v[0:1], s[42:43], v[0:1] op_sel_hi:[1,0]
	v_pk_mul_f32 v[2:3], v[2:3], v[86:87]
	v_pk_mul_f32 v[4:5], v[0:1], v[88:89]
	v_cvt_pk_bf16_f32 v0, v2, v3
	v_mul_f32_e32 v2, s44, v92
	v_cvt_pk_bf16_f32 v1, v4, v5
	v_pk_mul_f32 v[4:5], s[40:41], v[2:3] op_sel_hi:[1,0]
	v_pk_mul_f32 v[2:3], s[42:43], v[2:3] op_sel_hi:[1,0]
	v_pk_mul_f32 v[4:5], v[4:5], v[82:83]
	v_pk_mul_f32 v[6:7], v[2:3], v[84:85]
	v_cvt_pk_bf16_f32 v2, v4, v5
	v_mul_f32_e32 v4, s37, v92
	v_cvt_pk_bf16_f32 v3, v6, v7
	v_pk_mul_f32 v[6:7], s[40:41], v[4:5] op_sel_hi:[1,0]
	v_pk_mul_f32 v[4:5], s[42:43], v[4:5] op_sel_hi:[1,0]
	v_pk_mul_f32 v[6:7], v[6:7], v[78:79]
	v_pk_mul_f32 v[90:91], v[4:5], v[80:81]
	v_cvt_pk_bf16_f32 v4, v6, v7
	v_mul_f32_e32 v6, s36, v92
	v_cvt_pk_bf16_f32 v5, v90, v91
	v_pk_mul_f32 v[90:91], s[40:41], v[6:7] op_sel_hi:[1,0]
	v_pk_mul_f32 v[6:7], s[42:43], v[6:7] op_sel_hi:[1,0]
	v_pk_mul_f32 v[90:91], v[90:91], v[74:75]
	v_pk_mul_f32 v[92:93], v[6:7], v[76:77]
